# P8 tail task: four rows per trip with all loads in flight; P0 copy loops load their argument pointers once
# speedup vs baseline: 1.0068x; 1.0068x over previous
.LBB0_133:
	s_mov_b32 s2, 0x90000
	v_cmp_gt_i32_e32 vcc, s2, v0
	v_lshl_add_u32 v1, s12, 12, v58
	s_and_saveexec_b64 s[2:3], vcc
	s_cbranch_execz .LBB0_142
	s_load_dwordx4 s[44:47], s[26:27], 0x10
	s_waitcnt lgkmcnt(0)
	s_add_u32 s28, s18, 0x14900000
	s_addc_u32 s29, s19, 0
	s_add_u32 s30, s18, 0x1d300000
	s_addc_u32 s31, s19, 0
	v_lshl_add_u32 v8, s12, 12, v58
	s_lshl_b32 s9, s13, 12
	s_mov_b64 s[34:35], 0
	s_mov_b32 s11, 0x38e38e39
	s_mov_b64 s[36:37], 0x4000000
	s_movk_i32 s15, 0x1ff
	s_movk_i32 s42, 0x21f
	s_mov_b32 s4, 0
	s_mov_b32 s43, 0x8ffff
	v_mov_b32_e32 v9, v0
	s_branch .LBB0_136

.LBB0_140:
	s_andn2_saveexec_b64 s[6:7], s[38:39]
	s_cbranch_execz .LBB0_135
	v_ashrrev_i32_e32 v7, 31, v6
	v_lshlrev_b64 v[6:7], 19, v[6:7]
	v_lshlrev_b64 v[4:5], 10, v[4:5]
	v_lshl_add_u64 v[4:5], v[6:7], 0, v[4:5]
	v_or_b32_e32 v4, v4, v10
	v_lshlrev_b64 v[14:15], 2, v[4:5]
	s_waitcnt lgkmcnt(0)
	v_lshl_add_u64 v[16:17], s[44:45], 0, v[14:15]
	v_lshl_add_u64 v[14:15], s[46:47], 0, v[14:15]
	global_load_dwordx4 v[4:7], v[16:17], off
	global_load_dwordx4 v[10:13], v[16:17], off offset:16
	global_load_dwordx4 v[18:21], v[14:15], off
	global_load_dwordx4 v[14:17], v[14:15], off offset:16
	v_lshlrev_b64 v[2:3], 1, v[2:3]
	s_waitcnt vmcnt(3)
	v_cvt_pk_bf16_f32 v4, v4, v5
	v_cvt_pk_bf16_f32 v5, v6, v7
	s_waitcnt vmcnt(2)
	v_cvt_pk_bf16_f32 v6, v10, v11
	v_cvt_pk_bf16_f32 v7, v12, v13
	v_lshl_add_u64 v[10:11], s[28:29], 0, v[2:3]
	global_store_dwordx4 v[10:11], v[4:7], off
	v_lshl_add_u64 v[2:3], s[30:31], 0, v[2:3]
	s_waitcnt vmcnt(2)
	v_cvt_pk_bf16_f32 v18, v18, v19
	v_cvt_pk_bf16_f32 v19, v20, v21
	s_waitcnt vmcnt(1)
	v_cvt_pk_bf16_f32 v20, v14, v15
	v_cvt_pk_bf16_f32 v21, v16, v17
	global_store_dwordx4 v[2:3], v[18:21], off
	s_branch .LBB0_135
.LBB0_142:
	s_or_b64 exec, exec, s[2:3]
	s_mov_b32 s2, 0x84000
	v_cmp_gt_i32_e32 vcc, s2, v0
	s_and_saveexec_b64 s[2:3], vcc
	s_cbranch_execz .LBB0_151
	s_load_dwordx2 s[44:45], s[26:27], 0x20
	s_waitcnt lgkmcnt(0)
	s_add_u32 s4, s18, 0x9900000
	v_mov_b32_e32 v3, 0
	s_addc_u32 s5, s19, 0
	v_lshl_add_u32 v10, s12, 12, v58
	s_lshl_b32 s9, s13, 12
	s_mov_b64 s[6:7], 0
	s_mov_b32 s11, 0x3e0f83e1
	s_mov_b64 s[28:29], 0x1000000
	s_movk_i32 s15, 0x7ff
	s_movk_i32 s36, 0x81f
	s_mov_b32 s37, 0x83fff
	v_mov_b32_e32 v12, v3
	v_mov_b32_e32 v13, v3
	v_mov_b32_e32 v14, v3
	v_mov_b32_e32 v15, v3
	v_mov_b32_e32 v11, v0
	s_branch .LBB0_145

.LBB0_149:
	s_andn2_saveexec_b64 s[30:31], s[30:31]
	s_cbranch_execz .LBB0_144
	v_ashrrev_i32_e32 v7, 31, v6
	v_lshlrev_b64 v[6:7], 21, v[6:7]
	v_lshlrev_b64 v[8:9], 10, v[8:9]
	v_lshlrev_b32_e32 v2, 2, v2
	s_waitcnt lgkmcnt(0)
	v_lshl_add_u64 v[6:7], s[44:45], 0, v[6:7]
	v_lshl_add_u64 v[6:7], v[6:7], 0, v[8:9]
	v_lshl_add_u64 v[20:21], v[6:7], 0, v[2:3]
	global_load_dwordx4 v[6:9], v[20:21], off
	global_load_dwordx4 v[16:19], v[20:21], off offset:16
	v_lshl_add_u64 v[20:21], v[4:5], 1, s[4:5]
	s_waitcnt vmcnt(1)
	v_cvt_pk_bf16_f32 v4, v6, v7
	v_cvt_pk_bf16_f32 v5, v8, v9
	s_waitcnt vmcnt(0)
	v_cvt_pk_bf16_f32 v6, v16, v17
	v_cvt_pk_bf16_f32 v7, v18, v19
	global_store_dwordx4 v[20:21], v[4:7], off
	s_branch .LBB0_144

.Lt4i0_1251:
	s_or_b64 exec, exec, s[40:41]
	s_add_u32 s36, s8, s36
	s_addc_u32 s37, s9, s37
	s_lshl_b64 s[34:35], s[34:35], 10
	s_add_u32 s34, s36, s34
	s_addc_u32 s35, s37, s35
	s_lshl_b64 s[36:37], s[16:17], 2
	s_add_u32 s36, s42, s36
	s_addc_u32 s37, s43, s37
	global_load_dword v35, v1, s[36:37]
	s_add_i32 s16, s47, s48
	s_add_i32 s16, s16, 8
	s_cmpk_gt_u32 s16, 0xffff
	s_mov_b64 s[30:31], -1
	s_cbranch_scc0 .Lt4i1_1246
	s_add_i32 s34, s16, 0xffff0000
	s_lshr_b32 s11, s34, 5
	s_and_b32 s10, s16, 31
	s_mul_hi_u32 s28, s11, 0x840
	s_mulk_i32 s11, 0x840
	s_or_b32 s49, s10, 0x800
	s_or_b32 s10, s11, s10
	s_add_u32 s10, s10, 0x10800
	s_mov_b32 s35, s17
	s_addc_u32 s11, s28, 0
	s_lshl_b64 s[28:29], s[34:35], 7
	s_mov_b64 s[30:31], 0

.Lt4i1_1249:
	s_lshl_b64 s[40:41], s[10:11], 9
	s_waitcnt lgkmcnt(0)
	v_lshl_add_u64 v[46:47], v[2:3], 0, s[40:41]
	global_load_dwordx2 v[46:47], v[46:47], off
	v_mov_b32_e32 v0, 0
	v_mov_b32_e32 v48, 0
	v_mov_b32_e32 v49, 0
	s_and_saveexec_b64 s[40:41], s[4:5]
	s_cbranch_execz .Lt4i1_1251
	v_lshl_add_u64 v[32:33], v[4:5], 0, s[38:39]
	global_load_dword v48, v[32:33], off
	global_load_dword v49, v[6:7], off
	v_lshl_or_b32 v42, s49, 5, v12
	v_mov_b32_e32 v43, 0
	v_lshl_add_u64 v[44:45], v[42:43], 2, s[18:19]
	global_load_dword v50, v[44:45], off offset:64
	global_load_dword v51, v[44:45], off
.Lt4i1_1251:
	s_or_b64 exec, exec, s[40:41]
	s_add_u32 s36, s8, s36
	s_addc_u32 s37, s9, s37
	s_lshl_b64 s[34:35], s[34:35], 10
	s_add_u32 s34, s36, s34
	s_addc_u32 s35, s37, s35
	s_lshl_b64 s[36:37], s[16:17], 2
	s_add_u32 s36, s42, s36
	s_addc_u32 s37, s43, s37
	global_load_dword v52, v1, s[36:37]
	s_add_i32 s16, s47, s48
	s_add_i32 s16, s16, 16
	s_cmpk_gt_u32 s16, 0xffff
	s_mov_b64 s[30:31], -1
	s_cbranch_scc0 .Lt4i2_1246
	s_add_i32 s34, s16, 0xffff0000
	s_lshr_b32 s11, s34, 5
	s_and_b32 s10, s16, 31
	s_mul_hi_u32 s28, s11, 0x840
	s_mulk_i32 s11, 0x840
	s_or_b32 s49, s10, 0x800
	s_or_b32 s10, s11, s10
	s_add_u32 s10, s10, 0x10800
	s_mov_b32 s35, s17
	s_addc_u32 s11, s28, 0
	s_lshl_b64 s[28:29], s[34:35], 7
	s_mov_b64 s[30:31], 0

.Lt4i2_1249:
	s_lshl_b64 s[40:41], s[10:11], 9
	s_waitcnt lgkmcnt(0)
	v_lshl_add_u64 v[54:55], v[2:3], 0, s[40:41]
	global_load_dwordx2 v[54:55], v[54:55], off
	v_mov_b32_e32 v0, 0
	v_mov_b32_e32 v56, 0
	v_mov_b32_e32 v57, 0
	s_and_saveexec_b64 s[40:41], s[4:5]
	s_cbranch_execz .Lt4i2_1251
	v_lshl_add_u64 v[32:33], v[4:5], 0, s[38:39]
	global_load_dword v56, v[32:33], off
	global_load_dword v57, v[6:7], off
	v_lshl_or_b32 v42, s49, 5, v12
	v_mov_b32_e32 v43, 0
	v_lshl_add_u64 v[44:45], v[42:43], 2, s[18:19]
	global_load_dword v58, v[44:45], off offset:64
	global_load_dword v59, v[44:45], off
.Lt4i2_1251:
	s_or_b64 exec, exec, s[40:41]
	s_add_u32 s36, s8, s36
	s_addc_u32 s37, s9, s37
	s_lshl_b64 s[34:35], s[34:35], 10
	s_add_u32 s34, s36, s34
	s_addc_u32 s35, s37, s35
	s_lshl_b64 s[36:37], s[16:17], 2
	s_add_u32 s36, s42, s36
	s_addc_u32 s37, s43, s37
	global_load_dword v60, v1, s[36:37]
	s_add_i32 s16, s47, s48
	s_add_i32 s16, s16, 24
	s_cmpk_gt_u32 s16, 0xffff
	s_mov_b64 s[30:31], -1
	s_cbranch_scc0 .Lt4i3_1246
	s_add_i32 s34, s16, 0xffff0000
	s_lshr_b32 s11, s34, 5
	s_and_b32 s10, s16, 31
	s_mul_hi_u32 s28, s11, 0x840
	s_mulk_i32 s11, 0x840
	s_or_b32 s49, s10, 0x800
	s_or_b32 s10, s11, s10
	s_add_u32 s10, s10, 0x10800
	s_mov_b32 s35, s17
	s_addc_u32 s11, s28, 0
	s_lshl_b64 s[28:29], s[34:35], 7
	s_mov_b64 s[30:31], 0

.Lt4i3_1249:
	s_lshl_b64 s[40:41], s[10:11], 9
	s_waitcnt lgkmcnt(0)
	v_lshl_add_u64 v[62:63], v[2:3], 0, s[40:41]
	global_load_dwordx2 v[62:63], v[62:63], off
	v_mov_b32_e32 v0, 0
	v_mov_b32_e32 v64, 0
	v_mov_b32_e32 v65, 0
	s_and_saveexec_b64 s[40:41], s[4:5]
	s_cbranch_execz .Lt4i3_1251
	v_lshl_add_u64 v[32:33], v[4:5], 0, s[38:39]
	global_load_dword v64, v[32:33], off
	global_load_dword v65, v[6:7], off
	v_lshl_or_b32 v42, s49, 5, v12
	v_mov_b32_e32 v43, 0
	v_lshl_add_u64 v[44:45], v[42:43], 2, s[18:19]
	global_load_dword v66, v[44:45], off offset:64
	global_load_dword v67, v[44:45], off
.Lt4i3_1251:
	s_or_b64 exec, exec, s[40:41]
	s_add_u32 s36, s8, s36
	s_addc_u32 s37, s9, s37
	s_lshl_b64 s[34:35], s[34:35], 10
	s_add_u32 s34, s36, s34
	s_addc_u32 s35, s37, s35
	s_lshl_b64 s[36:37], s[16:17], 2
	s_add_u32 s36, s42, s36
	s_addc_u32 s37, s43, s37
	global_load_dword v68, v1, s[36:37]
	s_add_i32 s16, s47, s48
	s_cmpk_gt_u32 s16, 0xffff
	s_mov_b64 s[30:31], -1
	s_cbranch_scc0 .Lt4r0_1246
	s_add_i32 s34, s16, 0xffff0000
	s_lshr_b32 s11, s34, 5
	s_and_b32 s10, s16, 31
	s_mul_hi_u32 s28, s11, 0x840
	s_mulk_i32 s11, 0x840
	s_or_b32 s49, s10, 0x800
	s_or_b32 s10, s11, s10
	s_add_u32 s10, s10, 0x10800
	s_mov_b32 s35, s17
	s_addc_u32 s11, s28, 0
	s_lshl_b64 s[28:29], s[34:35], 7
	s_mov_b64 s[30:31], 0

.Lt4r0_1251:
	s_add_u32 s36, s8, s36
	s_addc_u32 s37, s9, s37
	s_lshl_b64 s[34:35], s[34:35], 10
	s_add_u32 s34, s36, s34
	s_addc_u32 s35, s37, s35
	s_lshl_b64 s[36:37], s[16:17], 2
	s_add_u32 s36, s42, s36
	s_addc_u32 s37, s43, s37
	s_waitcnt vmcnt(22)
	v_mul_f32_e32 v36, v31, v31
	v_lshlrev_b32_e32 v34, 16, v11
	v_lshlrev_b32_e32 v32, 16, v10
	v_and_b32_e32 v33, 0xffff0000, v10
	v_add_f32_dpp v36, v36, v36 quad_perm:[1,0,3,2] row_mask:0xf bank_mask:0xf
	s_nop 1
	v_add_f32_dpp v36, v36, v36 quad_perm:[2,3,0,1] row_mask:0xf bank_mask:0xf
	s_nop 1
	v_add_f32_dpp v36, v36, v36 row_half_mirror row_mask:0xf bank_mask:0xf
	s_nop 1
	v_add_f32_dpp v36, v36, v36 row_mirror row_mask:0xf bank_mask:0xf
	ds_bpermute_b32 v37, v29, v36
	s_waitcnt lgkmcnt(0)
	v_add_f32_e32 v10, v36, v37
	s_waitcnt vmcnt(18)
	v_fmamk_f32 v35, v35, 0x3b800000, v14
	v_mul_f32_e32 v37, 0x4b800000, v35
	v_cmp_gt_f32_e32 vcc, s46, v35
	s_nop 1
	v_cndmask_b32_e32 v35, v35, v37, vcc
	v_rsq_f32_e32 v37, v35
	v_and_b32_e32 v35, 0xffff0000, v11
	v_mul_f32_e32 v36, 0x45800000, v37
	v_cndmask_b32_e32 v36, v37, v36, vcc
	v_pk_mul_f32 v[34:35], v[36:37], v[34:35] op_sel_hi:[0,1]
	v_pk_mul_f32 v[32:33], v[36:37], v[32:33] op_sel_hi:[0,1]
	global_store_dwordx4 v15, v[32:35], s[34:35] nt
	v_fmamk_f32 v10, v10, 0x3d000000, v14
	v_mul_f32_e32 v11, 0x4b800000, v10
	v_cmp_gt_f32_e32 vcc, s46, v10
	s_nop 1
	v_cndmask_b32_e32 v10, v10, v11, vcc
	v_rsq_f32_e32 v10, v10
	s_nop 0
	v_mul_f32_e32 v11, 0x45800000, v10
	v_cndmask_b32_e32 v10, v10, v11, vcc
	v_mul_f32_e32 v10, v31, v10
	s_waitcnt vmcnt(19)
	v_mul_f32_e32 v10, v10, v38
	ds_bpermute_b32 v11, v29, v10
	s_and_saveexec_b64 s[34:35], s[4:5]
	s_cbranch_execz .Lt4_end0
	s_add_u32 s16, s8, s30
	s_addc_u32 s30, s9, s31
	s_add_u32 s28, s16, s28
	s_addc_u32 s29, s30, s29
	s_lshl_b64 s[10:11], s[10:11], 6
	s_waitcnt vmcnt(19) lgkmcnt(0)
	v_mul_f32_e32 v0, v39, v11
	v_cndmask_b32_e64 v0, v0, -v0, s[6:7]
	s_waitcnt vmcnt(19)
	v_fmac_f32_e32 v0, v10, v40
	global_store_dword v16, v0, s[28:29]
	v_cvt_pk_bf16_f32 v0, v0, s0
	v_lshl_add_u64 v[10:11], v[8:9], 0, s[10:11]
	global_store_short v[10:11], v0, off
.Lt4_end0:
	s_or_b64 exec, exec, s[34:35]
	s_add_i32 s16, s47, s48
	s_add_i32 s16, s16, 8
	s_cmpk_gt_u32 s16, 0xffff
	s_mov_b64 s[30:31], -1
	s_cbranch_scc0 .Lt4r1_1246
	s_add_i32 s34, s16, 0xffff0000
	s_lshr_b32 s11, s34, 5
	s_and_b32 s10, s16, 31
	s_mul_hi_u32 s28, s11, 0x840
	s_mulk_i32 s11, 0x840
	s_or_b32 s49, s10, 0x800
	s_or_b32 s10, s11, s10
	s_add_u32 s10, s10, 0x10800
	s_mov_b32 s35, s17
	s_addc_u32 s11, s28, 0
	s_lshl_b64 s[28:29], s[34:35], 7
	s_mov_b64 s[30:31], 0

.Lt4r1_1251:
	s_add_u32 s36, s8, s36
	s_addc_u32 s37, s9, s37
	s_lshl_b64 s[34:35], s[34:35], 10
	s_add_u32 s34, s36, s34
	s_addc_u32 s35, s37, s35
	s_lshl_b64 s[36:37], s[16:17], 2
	s_add_u32 s36, s42, s36
	s_addc_u32 s37, s43, s37
	s_waitcnt vmcnt(19)
	v_mul_f32_e32 v36, v48, v48
	v_lshlrev_b32_e32 v34, 16, v47
	v_lshlrev_b32_e32 v32, 16, v46
	v_and_b32_e32 v33, 0xffff0000, v46
	v_add_f32_dpp v36, v36, v36 quad_perm:[1,0,3,2] row_mask:0xf bank_mask:0xf
	s_nop 1
	v_add_f32_dpp v36, v36, v36 quad_perm:[2,3,0,1] row_mask:0xf bank_mask:0xf
	s_nop 1
	v_add_f32_dpp v36, v36, v36 row_half_mirror row_mask:0xf bank_mask:0xf
	s_nop 1
	v_add_f32_dpp v36, v36, v36 row_mirror row_mask:0xf bank_mask:0xf
	ds_bpermute_b32 v37, v29, v36
	s_waitcnt lgkmcnt(0)
	v_add_f32_e32 v46, v36, v37
	s_waitcnt vmcnt(15)
	v_fmamk_f32 v35, v52, 0x3b800000, v14
	v_mul_f32_e32 v37, 0x4b800000, v35
	v_cmp_gt_f32_e32 vcc, s46, v35
	s_nop 1
	v_cndmask_b32_e32 v35, v35, v37, vcc
	v_rsq_f32_e32 v37, v35
	v_and_b32_e32 v35, 0xffff0000, v47
	v_mul_f32_e32 v36, 0x45800000, v37
	v_cndmask_b32_e32 v36, v37, v36, vcc
	v_pk_mul_f32 v[34:35], v[36:37], v[34:35] op_sel_hi:[0,1]
	v_pk_mul_f32 v[32:33], v[36:37], v[32:33] op_sel_hi:[0,1]
	global_store_dwordx4 v15, v[32:35], s[34:35] nt
	v_fmamk_f32 v46, v46, 0x3d000000, v14
	v_mul_f32_e32 v47, 0x4b800000, v46
	v_cmp_gt_f32_e32 vcc, s46, v46
	s_nop 1
	v_cndmask_b32_e32 v46, v46, v47, vcc
	v_rsq_f32_e32 v46, v46
	s_nop 0
	v_mul_f32_e32 v47, 0x45800000, v46
	v_cndmask_b32_e32 v46, v46, v47, vcc
	v_mul_f32_e32 v46, v48, v46
	s_waitcnt vmcnt(16)
	v_mul_f32_e32 v46, v46, v49
	ds_bpermute_b32 v47, v29, v46
	s_and_saveexec_b64 s[34:35], s[4:5]
	s_cbranch_execz .Lt4_end1
	s_add_u32 s16, s8, s30
	s_addc_u32 s30, s9, s31
	s_add_u32 s28, s16, s28
	s_addc_u32 s29, s30, s29
	s_lshl_b64 s[10:11], s[10:11], 6
	s_waitcnt vmcnt(16) lgkmcnt(0)
	v_mul_f32_e32 v0, v50, v47
	v_cndmask_b32_e64 v0, v0, -v0, s[6:7]
	s_waitcnt vmcnt(16)
	v_fmac_f32_e32 v0, v46, v51
	global_store_dword v16, v0, s[28:29]
	v_cvt_pk_bf16_f32 v0, v0, s0
	v_lshl_add_u64 v[46:47], v[8:9], 0, s[10:11]
	global_store_short v[46:47], v0, off
.Lt4_end1:
	s_or_b64 exec, exec, s[34:35]
	s_add_i32 s16, s47, s48
	s_add_i32 s16, s16, 16
	s_cmpk_gt_u32 s16, 0xffff
	s_mov_b64 s[30:31], -1
	s_cbranch_scc0 .Lt4r2_1246
	s_add_i32 s34, s16, 0xffff0000
	s_lshr_b32 s11, s34, 5
	s_and_b32 s10, s16, 31
	s_mul_hi_u32 s28, s11, 0x840
	s_mulk_i32 s11, 0x840
	s_or_b32 s49, s10, 0x800
	s_or_b32 s10, s11, s10
	s_add_u32 s10, s10, 0x10800
	s_mov_b32 s35, s17
	s_addc_u32 s11, s28, 0
	s_lshl_b64 s[28:29], s[34:35], 7
	s_mov_b64 s[30:31], 0

.Lt4r2_1251:
	s_add_u32 s36, s8, s36
	s_addc_u32 s37, s9, s37
	s_lshl_b64 s[34:35], s[34:35], 10
	s_add_u32 s34, s36, s34
	s_addc_u32 s35, s37, s35
	s_lshl_b64 s[36:37], s[16:17], 2
	s_add_u32 s36, s42, s36
	s_addc_u32 s37, s43, s37
	s_waitcnt vmcnt(16)
	v_mul_f32_e32 v36, v56, v56
	v_lshlrev_b32_e32 v34, 16, v55
	v_lshlrev_b32_e32 v32, 16, v54
	v_and_b32_e32 v33, 0xffff0000, v54
	v_add_f32_dpp v36, v36, v36 quad_perm:[1,0,3,2] row_mask:0xf bank_mask:0xf
	s_nop 1
	v_add_f32_dpp v36, v36, v36 quad_perm:[2,3,0,1] row_mask:0xf bank_mask:0xf
	s_nop 1
	v_add_f32_dpp v36, v36, v36 row_half_mirror row_mask:0xf bank_mask:0xf
	s_nop 1
	v_add_f32_dpp v36, v36, v36 row_mirror row_mask:0xf bank_mask:0xf
	ds_bpermute_b32 v37, v29, v36
	s_waitcnt lgkmcnt(0)
	v_add_f32_e32 v54, v36, v37
	s_waitcnt vmcnt(12)
	v_fmamk_f32 v35, v60, 0x3b800000, v14
	v_mul_f32_e32 v37, 0x4b800000, v35
	v_cmp_gt_f32_e32 vcc, s46, v35
	s_nop 1
	v_cndmask_b32_e32 v35, v35, v37, vcc
	v_rsq_f32_e32 v37, v35
	v_and_b32_e32 v35, 0xffff0000, v55
	v_mul_f32_e32 v36, 0x45800000, v37
	v_cndmask_b32_e32 v36, v37, v36, vcc
	v_pk_mul_f32 v[34:35], v[36:37], v[34:35] op_sel_hi:[0,1]
	v_pk_mul_f32 v[32:33], v[36:37], v[32:33] op_sel_hi:[0,1]
	global_store_dwordx4 v15, v[32:35], s[34:35] nt
	v_fmamk_f32 v54, v54, 0x3d000000, v14
	v_mul_f32_e32 v55, 0x4b800000, v54
	v_cmp_gt_f32_e32 vcc, s46, v54
	s_nop 1
	v_cndmask_b32_e32 v54, v54, v55, vcc
	v_rsq_f32_e32 v54, v54
	s_nop 0
	v_mul_f32_e32 v55, 0x45800000, v54
	v_cndmask_b32_e32 v54, v54, v55, vcc
	v_mul_f32_e32 v54, v56, v54
	s_waitcnt vmcnt(13)
	v_mul_f32_e32 v54, v54, v57
	ds_bpermute_b32 v55, v29, v54
	s_and_saveexec_b64 s[34:35], s[4:5]
	s_cbranch_execz .Lt4_end2
	s_add_u32 s16, s8, s30
	s_addc_u32 s30, s9, s31
	s_add_u32 s28, s16, s28
	s_addc_u32 s29, s30, s29
	s_lshl_b64 s[10:11], s[10:11], 6
	s_waitcnt vmcnt(13) lgkmcnt(0)
	v_mul_f32_e32 v0, v58, v55
	v_cndmask_b32_e64 v0, v0, -v0, s[6:7]
	s_waitcnt vmcnt(13)
	v_fmac_f32_e32 v0, v54, v59
	global_store_dword v16, v0, s[28:29]
	v_cvt_pk_bf16_f32 v0, v0, s0
	v_lshl_add_u64 v[54:55], v[8:9], 0, s[10:11]
	global_store_short v[54:55], v0, off
.Lt4_end2:
	s_or_b64 exec, exec, s[34:35]
	s_add_i32 s16, s47, s48
	s_add_i32 s16, s16, 24
	s_cmpk_gt_u32 s16, 0xffff
	s_mov_b64 s[30:31], -1
	s_cbranch_scc0 .Lt4r3_1246
	s_add_i32 s34, s16, 0xffff0000
	s_lshr_b32 s11, s34, 5
	s_and_b32 s10, s16, 31
	s_mul_hi_u32 s28, s11, 0x840
	s_mulk_i32 s11, 0x840
	s_or_b32 s49, s10, 0x800
	s_or_b32 s10, s11, s10
	s_add_u32 s10, s10, 0x10800
	s_mov_b32 s35, s17
	s_addc_u32 s11, s28, 0
	s_lshl_b64 s[28:29], s[34:35], 7
	s_mov_b64 s[30:31], 0

.Lt4r3_1251:
	s_add_u32 s36, s8, s36
	s_addc_u32 s37, s9, s37
	s_lshl_b64 s[34:35], s[34:35], 10
	s_add_u32 s34, s36, s34
	s_addc_u32 s35, s37, s35
	s_lshl_b64 s[36:37], s[16:17], 2
	s_add_u32 s36, s42, s36
	s_addc_u32 s37, s43, s37
	s_waitcnt vmcnt(13)
	v_mul_f32_e32 v36, v64, v64
	v_lshlrev_b32_e32 v34, 16, v63
	v_lshlrev_b32_e32 v32, 16, v62
	v_and_b32_e32 v33, 0xffff0000, v62
	v_add_f32_dpp v36, v36, v36 quad_perm:[1,0,3,2] row_mask:0xf bank_mask:0xf
	s_nop 1
	v_add_f32_dpp v36, v36, v36 quad_perm:[2,3,0,1] row_mask:0xf bank_mask:0xf
	s_nop 1
	v_add_f32_dpp v36, v36, v36 row_half_mirror row_mask:0xf bank_mask:0xf
	s_nop 1
	v_add_f32_dpp v36, v36, v36 row_mirror row_mask:0xf bank_mask:0xf
	ds_bpermute_b32 v37, v29, v36
	s_waitcnt lgkmcnt(0)
	v_add_f32_e32 v62, v36, v37
	s_waitcnt vmcnt(9)
	v_fmamk_f32 v35, v68, 0x3b800000, v14
	v_mul_f32_e32 v37, 0x4b800000, v35
	v_cmp_gt_f32_e32 vcc, s46, v35
	s_nop 1
	v_cndmask_b32_e32 v35, v35, v37, vcc
	v_rsq_f32_e32 v37, v35
	v_and_b32_e32 v35, 0xffff0000, v63
	v_mul_f32_e32 v36, 0x45800000, v37
	v_cndmask_b32_e32 v36, v37, v36, vcc
	v_pk_mul_f32 v[34:35], v[36:37], v[34:35] op_sel_hi:[0,1]
	v_pk_mul_f32 v[32:33], v[36:37], v[32:33] op_sel_hi:[0,1]
	global_store_dwordx4 v15, v[32:35], s[34:35] nt
	v_fmamk_f32 v62, v62, 0x3d000000, v14
	v_mul_f32_e32 v63, 0x4b800000, v62
	v_cmp_gt_f32_e32 vcc, s46, v62
	s_nop 1
	v_cndmask_b32_e32 v62, v62, v63, vcc
	v_rsq_f32_e32 v62, v62
	s_nop 0
	v_mul_f32_e32 v63, 0x45800000, v62
	v_cndmask_b32_e32 v62, v62, v63, vcc
	v_mul_f32_e32 v62, v64, v62
	s_waitcnt vmcnt(10)
	v_mul_f32_e32 v62, v62, v65
	ds_bpermute_b32 v63, v29, v62
	s_and_saveexec_b64 s[34:35], s[4:5]
	s_cbranch_execz .Lt4_end3
	s_add_u32 s16, s8, s30
	s_addc_u32 s30, s9, s31
	s_add_u32 s28, s16, s28
	s_addc_u32 s29, s30, s29
	s_lshl_b64 s[10:11], s[10:11], 6
	s_waitcnt vmcnt(10) lgkmcnt(0)
	v_mul_f32_e32 v0, v66, v63
	v_cndmask_b32_e64 v0, v0, -v0, s[6:7]
	s_waitcnt vmcnt(10)
	v_fmac_f32_e32 v0, v62, v67
	global_store_dword v16, v0, s[28:29]
	v_cvt_pk_bf16_f32 v0, v0, s0
	v_lshl_add_u64 v[62:63], v[8:9], 0, s[10:11]
	global_store_short v[62:63], v0, off
.Lt4_end3:
	s_or_b64 exec, exec, s[34:35]
	s_add_i32 s48, s48, 32
	s_cmpk_eq_i32 s48, 0x80
	s_cbranch_scc1 .LBB0_1235
	s_branch .LBB0_1244
